# combo13: combo11 + in P3 the workgroups with bit 3 of blockIdx set run GLA pass C (memory-bound) before attention (compute-bound) instead of after, so the two kinds of work overlap across the chip
# speedup vs baseline: 1.0015x; 1.0015x over previous
; #define GSYNC() xcd_barrier(xbar)
; #define GSYNC() grid.sync()
; #define REPEAT(k) _Pragma("unroll 1") for (int rep_ = 0, nrep_ = opaque_int((((REP) >> (k)) & 1) + 1); rep_ < nrep_; ++rep_)
; __device__ __forceinline__ void attn_phase(char* lds, const bf16* Q, const bf16* K, const bf16* V, bf16* mixed) {
;     for (int L = blockIdx.x; L < 256; L += GRID) {
;         const Item it = decode(L);
;         attn_block(mkref(it, 0, Q, K, V, mixed), lds);
;         attn_block(mkref(it, 1, Q, K, V, mixed), lds);
;     }
; __global__ void __launch_bounds__(512, 2) mega_fwd(Args a) {
;     ...
;         GSYNC();
;     ...
;         REPEAT(8) att::attn_phase((char*)lds, (const att::bf16*)QB_, (const att::bf16*)KB_, (const att::bf16*)VB_, (att::bf16*)HN);
;     ...
;         __syncthreads();
;     ...
;         REPEAT(9) gla_pass_c(ldsl, PROJ, BT, GST, a.in[8] + l * 128, HN);
.LBB0_534:
	s_or_b64 exec, exec, s[0:1]
	s_and_b64 vcc, exec, s[4:5]
	s_mov_b32 s1, s66
	s_waitcnt lgkmcnt(0)
	s_barrier
	s_mov_b32 s2, 0
	v_writelane_b32 v255, s2, 40
	s_cbranch_vccnz .LBB0_535
	s_bitcmp1_b32 s66, 3
	s_cbranch_scc0 .LBB0_538
	s_mov_b32 s2, 1
	v_writelane_b32 v255, s2, 40
	v_readlane_b32 s54, v254, 23
	v_readlane_b32 s56, v254, 25
	v_readlane_b32 s58, v254, 27
	v_readlane_b32 s60, v254, 29
	v_readlane_b32 s64, v254, 49
	v_readlane_b32 s68, v254, 51
	v_readlane_b32 s80, v254, 32
	v_readlane_b32 s82, v254, 34
	v_readlane_b32 s84, v254, 36
	v_readlane_b32 s86, v254, 38
	v_readlane_b32 s92, v254, 40
	v_readlane_b32 s94, v254, 42
	v_readlane_b32 s96, v254, 44
	v_readlane_b32 s55, v254, 24
	v_readlane_b32 s57, v254, 26
	v_readlane_b32 s59, v254, 28
	v_readlane_b32 s61, v254, 30
	v_readlane_b32 s65, v254, 50
	v_readlane_b32 s69, v254, 52
	v_readlane_b32 s53, v254, 31
	v_readlane_b32 s81, v254, 33
	v_readlane_b32 s83, v254, 35
	v_readlane_b32 s85, v254, 37
	v_readlane_b32 s87, v254, 39
	v_readlane_b32 s93, v254, 41
	v_readlane_b32 s95, v254, 43
	v_readlane_b32 s97, v254, 45
	s_mov_b32 s51, 0x10000
	s_mov_b32 s52, 0x14000
	s_movk_i32 s49, 0x4000

; #define REPEAT(k) _Pragma("unroll 1") for (int rep_ = 0, nrep_ = opaque_int((((REP) >> (k)) & 1) + 1); rep_ < nrep_; ++rep_)
; __device__ __forceinline__ void attn_phase(char* lds, const bf16* Q, const bf16* K, const bf16* V, bf16* mixed) {
;     for (int L = blockIdx.x; L < 256; L += GRID) {
;         const Item it = decode(L);
;         attn_block(mkref(it, 0, Q, K, V, mixed), lds);
;         attn_block(mkref(it, 1, Q, K, V, mixed), lds);
;     }
; }
; __global__ void __launch_bounds__(512, 2) mega_fwd(Args a) {
;     ...
;         REPEAT(8) att::attn_phase((char*)lds, (const att::bf16*)QB_, (const att::bf16*)KB_, (const att::bf16*)VB_, (att::bf16*)HN);
;     ...
;         __syncthreads();
;     ...
;         REPEAT(9) gla_pass_c(ldsl, PROJ, BT, GST, a.in[8] + l * 128, HN);
.LBB0_537:
	s_or_b64 exec, exec, s[2:3]
	s_waitcnt vmcnt(0) lgkmcnt(0)
	s_barrier
	v_readlane_b32 s1, v255, 3
	s_add_i32 s0, s1, 0x100
	s_cmp_lt_i32 s1, 0
	s_mov_b32 s1, s0
	s_cbranch_scc1 .LBB0_538
	v_readlane_b32 s2, v255, 40
	s_cmp_eq_u32 s2, 2
	s_cbranch_scc0 .LBB0_535
	s_mov_b64 s[44:45], 0x2000
	s_mov_b64 s[70:71], 0x100000
	s_movk_i32 s67, 0x180
	s_mov_b32 s33, 0x18000
	s_mov_b32 s42, 0x8000
	s_branch .Lsw_end

; __device__ __forceinline__ unsigned xb_add(unsigned* p, unsigned v) { return __hip_atomic_fetch_add(p, v, __ATOMIC_RELAXED, __HIP_MEMORY_SCOPE_AGENT); }
; #define GSYNC() xcd_barrier(xbar)
; #define GSYNC() grid.sync()
; #define REPEAT(k) _Pragma("unroll 1") for (int rep_ = 0, nrep_ = opaque_int((((REP) >> (k)) & 1) + 1); rep_ < nrep_; ++rep_)
; __device__ __forceinline__ void xcd_barrier(const XcdBarrier& b) {
;     asm volatile("s_waitcnt vmcnt(0)" ::: "memory");
;     __syncthreads();
;     if (threadIdx.x == 0) {
;         unsigned* bar = b.bar; unsigned bx = b.x; asm volatile("" : "+s"(bx));
;         __builtin_amdgcn_s_waitcnt(0);
;         unsigned nloc = b.st[0], nx = b.st[1];
;         if (nloc == 0u) { xcd_barrier_complete(bar, bx, nloc, nx); b.st[0] = nloc; b.st[1] = nx; }
;         const unsigned old = xb_add(&bar[XB_XSUB(bx)], 1u);
;         const unsigned gen = old / nloc;
;         if (old + 1u == (gen + 1u) * nloc) {
; __global__ void __launch_bounds__(512, 2) mega_fwd(Args a) {
;     ...
;         REPEAT(8) att::attn_phase((char*)lds, (const att::bf16*)QB_, (const att::bf16*)KB_, (const att::bf16*)VB_, (att::bf16*)HN);
;     ...
;         __syncthreads();
;     ...
;         REPEAT(9) gla_pass_c(ldsl, PROJ, BT, GST, a.in[8] + l * 128, HN);
;     ...
;         GSYNC();
.LBB0_880:
	s_or_b64 exec, exec, s[0:1]
	v_readlane_b32 s2, v255, 40
	s_cmp_eq_u32 s2, 1
	s_cbranch_scc0 .Lsw_end
	s_mov_b32 s2, 2
	v_writelane_b32 v255, s2, 40
	s_mov_b32 s1, s66
	s_mov_b32 s67, 0x41000000
	s_waitcnt vmcnt(0) lgkmcnt(0)
	s_barrier
	s_branch .LBB0_538
.Lsw_end:
	s_waitcnt vmcnt(0)
	s_barrier
	s_mov_b64 s[0:1], exec
	v_readlane_b32 s2, v252, 3
	v_readlane_b32 s3, v252, 4
	s_and_b64 s[2:3], s[0:1], s[2:3]
	s_mov_b32 s26, 0xbfb8aa3b
	s_mov_b32 s27, 0x800000
	s_mov_b32 s28, 0x3f317217
	s_mov_b32 s29, 0x7f800000
	v_readlane_b32 s20, v254, 55
	v_readlane_b32 s21, v254, 56
	s_mov_b64 exec, s[2:3]
	s_cbranch_execz .LBB0_932
	s_waitcnt vmcnt(0) lgkmcnt(0)
	v_mov_b32_e32 v0, 0x26800
	ds_read_b32 v2, v0
	ds_read_b32 v3, v0 offset:4
	ds_read_b32 v8, v0 offset:8
	v_readlane_b32 s10, v252, 0
	v_readlane_b32 s11, v252, 1
	v_readlane_b32 s12, v252, 2
	s_lshl_b32 s12, s12, 8
	s_add_u32 s14, s10, s12
	s_addc_u32 s15, s11, 0
	s_add_u32 s14, s14, 0x1400
	s_addc_u32 s15, s15, 0
	s_add_u32 s16, s10, 0x3400
	s_addc_u32 s17, s11, 0
	v_mov_b32_e32 v4, 1
	global_atomic_add v5, v161, v4, s[14:15] sc0
	s_waitcnt lgkmcnt(0)
	v_readfirstlane_b32 s18, v2
	v_readfirstlane_b32 s19, v3
	v_cvt_f32_u32_e32 v7, v2
	v_rcp_f32_e32 v7, v7
	s_waitcnt vmcnt(0)
	v_readfirstlane_b32 s13, v5
	v_cvt_f32_u32_e32 v6, v5
	v_mul_f32_e32 v6, v6, v7
	v_cvt_u32_f32_e32 v6, v6
	s_nop 0
	v_readfirstlane_b32 s2, v6
	s_mul_i32 s3, s2, s18
	s_cmp_gt_u32 s3, s13
	s_cbranch_scc0 .Lxb3_a
	s_sub_i32 s2, s2, 1
	s_sub_i32 s3, s3, s18
